# grid seam after weight conversion uses the XCD-hierarchical barrier code instead of the single-counter grid sync; no grid barrier between first-half WO and second-half G1
# speedup vs baseline: 1.0178x; 1.0139x over previous
_Z8mega_fwd4Args:
	s_mov_b32 s101, 0
	s_load_dwordx8 s[64:71], s[0:1], 0x80
	s_load_dword s22, s[0:1], 0xa8
	s_load_dwordx2 s[74:75], s[0:1], 0xa0
	s_mov_b32 s72, s2
	s_add_u32 s2, s0, 0xa0
	s_addc_u32 s3, s1, 0
	v_and_b32_e32 v206, 0x3ff, v0
	v_writelane_b32 v248, s2, 0
	v_cmp_gt_u32_e32 vcc, 2, v206
	s_nop 0
	v_writelane_b32 v248, s3, 1
	s_and_saveexec_b64 s[2:3], vcc
	v_lshl_add_u32 v1, v206, 2, 0
	v_add_u32_e32 v1, 0x20c40, v1
	v_mov_b32_e32 v2, 0
	ds_write_b32 v1, v2
	s_or_b64 exec, exec, s[2:3]
	s_load_dwordx16 s[4:19], s[0:1], 0x0
	s_waitcnt lgkmcnt(0)
	s_barrier
	v_writelane_b32 v248, s4, 2
	s_nop 1
	v_writelane_b32 v248, s5, 3
	v_writelane_b32 v248, s6, 4
	v_writelane_b32 v248, s7, 5
	v_writelane_b32 v248, s8, 6
	v_writelane_b32 v248, s9, 7
	v_writelane_b32 v248, s10, 8
	v_writelane_b32 v248, s11, 9
	v_writelane_b32 v248, s12, 10
	v_writelane_b32 v248, s13, 11
	v_writelane_b32 v248, s14, 12
	v_writelane_b32 v248, s15, 13
	v_writelane_b32 v248, s16, 14
	v_writelane_b32 v248, s17, 15
	v_writelane_b32 v248, s18, 16
	v_writelane_b32 v248, s19, 17
	s_mov_b64 s[6:7], s[70:71]
	s_add_u32 s8, s6, 0x4000
	s_getreg_b32 s2, hwreg(HW_REG_XCC_ID, 0, 4)
	s_addc_u32 s9, s7, 0
	s_and_b32 s23, s2, 15
	v_cmp_eq_u32_e64 s[4:5], 0, v206
	s_mov_b64 s[2:3], exec
	s_nop 0
	v_writelane_b32 v248, s4, 18
	s_nop 1
	v_writelane_b32 v248, s5, 19
	s_and_b64 s[4:5], s[2:3], s[4:5]
	s_mov_b64 exec, s[4:5]
	s_cbranch_execz .LBB0_5
	s_mov_b64 s[4:5], exec
	v_mbcnt_lo_u32_b32 v1, s4, 0
	v_mbcnt_hi_u32_b32 v1, s5, v1
	v_cmp_eq_u32_e32 vcc, 0, v1
	s_and_b64 s[10:11], exec, vcc
	s_mov_b64 exec, s[10:11]
	s_cbranch_execz .LBB0_5
	s_lshl_b32 s10, s23, 8
	s_bcnt1_i32_b64 s4, s[4:5]
	v_mov_b32_e32 v1, s10
	v_mov_b32_e32 v2, s4
	global_atomic_add v1, v2, s[8:9] offset:1024

.LBB0_140:
	s_or_b64 exec, exec, s[0:1]
	s_xor_b64 s[0:1], s[4:5], -1
	s_waitcnt vmcnt(0) lgkmcnt(0)
	v_writelane_b32 v252, s0, 3
	s_barrier
	s_nop 0
	v_writelane_b32 v252, s1, 4
	v_writelane_b32 v255, s4, 9
	v_writelane_b32 v255, s5, 10
	v_writelane_b32 v255, s6, 11
	s_mov_b32 s101, 1
	s_branch .LBB0_255
.Lgsync_ret:
	s_or_b64 exec, exec, s[0:1]
	s_mov_b32 s101, 0
	v_readlane_b32 s4, v255, 9
	v_readlane_b32 s5, v255, 10
	v_readlane_b32 s6, v255, 11
	s_waitcnt lgkmcnt(0)
	s_barrier
	s_mov_b64 s[0:1], exec

.LBB0_307:
	s_cmp_eq_u32 s101, 1
	s_cbranch_scc1 .Lgsync_ret
	s_or_b64 exec, exec, s[0:1]
	s_xor_b64 s[0:1], s[2:3], -1
	v_writelane_b32 v252, s0, 10
	s_mov_b64 s[10:11], s[70:71]
	s_waitcnt lgkmcnt(0)
	v_writelane_b32 v252, s1, 11
	v_readlane_b32 s0, v249, 33
	v_readlane_b32 s1, v249, 34
	s_andn2_b64 vcc, exec, s[0:1]
	s_barrier
	v_cndmask_b32_e64 v1, 0, 1, s[0:1]
	v_cmp_ne_u32_e64 s[2:3], 1, v1
	s_nop 1
	v_writelane_b32 v252, s2, 12
	s_nop 1
	v_writelane_b32 v252, s3, 13
	s_cbranch_vccnz .LBB0_550
	s_add_u32 s12, s10, 0xb400000
	s_addc_u32 s13, s11, 0
	s_add_u32 s14, s10, 0x11400000
	v_readlane_b32 s16, v251, 14
	v_readlane_b32 s18, v250, 50
	v_readlane_b32 s20, v250, 46
	s_addc_u32 s15, s11, 0
	v_readlane_b32 s17, v251, 15
	v_readlane_b32 s19, v250, 51
	v_readlane_b32 s21, v250, 47
	v_readlane_b32 s22, v250, 45
	s_mov_b32 s23, s72
	s_branch .LBB0_310

.LBB0_978:
	s_waitcnt vmcnt(0)
	s_waitcnt lgkmcnt(0)
	s_barrier
	v_readlane_b32 s0, v252, 10
	v_readlane_b32 s1, v252, 11
	s_nop 0
	s_and_b64 vcc, exec, s[0:1]
	s_cbranch_vccnz .Lwo_sync
	s_mov_b64 s[0:1], exec
	s_branch .LBB0_152
.Lwo_sync:
	s_mov_b64 s[0:1], exec
	v_readlane_b32 s2, v248, 18
	v_readlane_b32 s3, v248, 19
	s_and_b64 s[2:3], s[0:1], s[2:3]
	s_mov_b64 exec, s[2:3]
	s_cbranch_execz .LBB0_152
	v_readlane_b32 s2, v251, 2
	s_waitcnt vmcnt(0) expcnt(0) lgkmcnt(0)
	s_nop 0
	v_mov_b32_e32 v1, s2
	ds_read_b32 v3, v1
	v_readlane_b32 s2, v251, 3
	s_waitcnt lgkmcnt(0)
	v_cmp_ne_u32_e32 vcc, 0, v3
	v_mov_b32_e32 v1, s2
	ds_read_b32 v2, v1
	s_cbranch_vccnz .LBB0_994
	s_mov_b32 s8, 1
	s_branch .LBB0_982

	.amdhsa_kernel _Z8mega_fwd4Args
		.amdhsa_group_segment_fixed_size 0
		.amdhsa_private_segment_fixed_size 0
		.amdhsa_kernarg_size 416
		.amdhsa_user_sgpr_count 2
		.amdhsa_user_sgpr_dispatch_ptr 0
		.amdhsa_user_sgpr_queue_ptr 0
		.amdhsa_user_sgpr_kernarg_segment_ptr 1
		.amdhsa_user_sgpr_dispatch_id 0
		.amdhsa_user_sgpr_kernarg_preload_length 0
		.amdhsa_user_sgpr_kernarg_preload_offset 0
		.amdhsa_user_sgpr_private_segment_size 0
		.amdhsa_uses_dynamic_stack 0
		.amdhsa_enable_private_segment 0
		.amdhsa_system_sgpr_workgroup_id_x 1
		.amdhsa_system_sgpr_workgroup_id_y 0
		.amdhsa_system_sgpr_workgroup_id_z 0
		.amdhsa_system_sgpr_workgroup_info 0
		.amdhsa_system_vgpr_workitem_id 2
		.amdhsa_next_free_vgpr 256
		.amdhsa_next_free_sgpr 102
		.amdhsa_accum_offset 256
		.amdhsa_reserve_vcc 1
		.amdhsa_float_round_mode_32 0
		.amdhsa_float_round_mode_16_64 0
		.amdhsa_float_denorm_mode_32 3
		.amdhsa_float_denorm_mode_16_64 3
		.amdhsa_dx10_clamp 1
		.amdhsa_ieee_mode 1
		.amdhsa_fp16_overflow 0
		.amdhsa_tg_split 0
		.amdhsa_exception_fp_ieee_invalid_op 0
		.amdhsa_exception_fp_denorm_src 0
		.amdhsa_exception_fp_ieee_div_zero 0
		.amdhsa_exception_fp_ieee_overflow 0
		.amdhsa_exception_fp_ieee_underflow 0
		.amdhsa_exception_fp_ieee_inexact 0
		.amdhsa_exception_int_div_zero 0
	.end_amdhsa_kernel

amdhsa.kernels:
  - .agpr_count:     0
    .args:
      - .offset:         0
        .size:           160
        .value_kind:     by_value
      - .offset:         160
        .size:           4
        .value_kind:     hidden_block_count_x
      - .offset:         164
        .size:           4
        .value_kind:     hidden_block_count_y
      - .offset:         168
        .size:           4
        .value_kind:     hidden_block_count_z
      - .offset:         172
        .size:           2
        .value_kind:     hidden_group_size_x
      - .offset:         174
        .size:           2
        .value_kind:     hidden_group_size_y
      - .offset:         176
        .size:           2
        .value_kind:     hidden_group_size_z
      - .offset:         178
        .size:           2
        .value_kind:     hidden_remainder_x
      - .offset:         180
        .size:           2
        .value_kind:     hidden_remainder_y
      - .offset:         182
        .size:           2
        .value_kind:     hidden_remainder_z
      - .offset:         200
        .size:           8
        .value_kind:     hidden_global_offset_x
      - .offset:         208
        .size:           8
        .value_kind:     hidden_global_offset_y
      - .offset:         216
        .size:           8
        .value_kind:     hidden_global_offset_z
      - .offset:         224
        .size:           2
        .value_kind:     hidden_grid_dims
      - .offset:         248
        .size:           8
        .value_kind:     hidden_multigrid_sync_arg
      - .offset:         280
        .size:           4
        .value_kind:     hidden_dynamic_lds_size
    .group_segment_fixed_size: 0
    .kernarg_segment_align: 8
    .kernarg_segment_size: 416
    .language:       OpenCL C
    .language_version:
      - 2
      - 0
    .max_flat_workgroup_size: 512
    .name:           _Z8mega_fwd4Args
    .private_segment_fixed_size: 0
    .sgpr_count:     108
    .sgpr_spill_count: 460
    .symbol:         _Z8mega_fwd4Args.kd
    .uniform_work_group_size: 1
    .uses_dynamic_stack: false
    .vgpr_count:     256
    .vgpr_spill_count: 0
    .wavefront_size: 64
